# stack: sgu LayerNorm loads and epilogue u/gate loads hoisted, pre-P1 768 / slot 1792 split, hot loop heads 64-byte aligned
# speedup vs baseline: 1.0103x; 1.0010x over previous
; __device__ __forceinline__ void mix_sgu(const bf16* h, const float* lng, const float* lnb, const float* sgw, const float* sgb, bf16* ycat, char* lds, int wg, int nwg) {
;     ...
;         for (int i = 0; i < 8; ++i) { const int idx = tid + 512 * i, t = idx >> 5, s4 = (idx & 31) * 4; const f32x4 w = *(const f32x4*)(sgw + (size_t)grp * 16384 + t * 128 + s4);
;             typedef _Float16 h4 __attribute__((ext_vector_type(4))); h4 o; o[0] = (_Float16)(s4 <= t ? w[0] : 0.f); o[1] = (_Float16)(s4 + 1 <= t ? w[1] : 0.f); o[2] = (_Float16)(s4 + 2 <= t ? w[2] : 0.f); o[3] = (_Float16)(s4 + 3 <= t ? w[3] : 0.f); *(h4*)(lds + t * 288 + s4 * 2) = o; }
;         { const int row = tid >> 2, q = tid & 3; const bf16* vr = h + (m0 + row) * NH + C_DV;
;           float s1 = 0.f, s2 = 0.f;
; #pragma unroll
;           for (int j = 0; j < 16; ++j) { const v4u vv = *(const v4u*)(vr + (4 * j + q) * 8);
.LBB0_676:
	s_and_b32 s27, s26, 3
	s_lshl_b32 s28, s27, 16
	v_lshl_add_u64 v[28:29], v[32:33], 0, s[28:29]
	v_lshl_add_u64 v[0:1], v[40:41], 2, v[28:29]
	global_load_dwordx4 v[0:3], v[0:1], off
	v_lshl_add_u64 v[4:5], v[42:43], 2, v[28:29]
	v_lshl_add_u64 v[8:9], v[44:45], 2, v[28:29]
	v_lshl_add_u64 v[12:13], v[46:47], 2, v[28:29]
	v_lshl_add_u64 v[16:17], v[48:49], 2, v[28:29]
	v_lshl_add_u64 v[20:21], v[50:51], 2, v[28:29]
	global_load_dwordx4 v[4:7], v[4:5], off
	v_lshl_add_u64 v[24:25], v[52:53], 2, v[28:29]
	global_load_dwordx4 v[8:11], v[8:9], off
	v_lshl_add_u64 v[28:29], v[54:55], 2, v[28:29]
	global_load_dwordx4 v[12:15], v[12:13], off
	v_readlane_b32 s40, v255, 56
	global_load_dwordx4 v[16:19], v[16:17], off
	v_readlane_b32 s41, v255, 57
	global_load_dwordx4 v[20:23], v[20:21], off
	s_ashr_i32 s24, s26, 7
	global_load_dwordx4 v[24:27], v[24:25], off
	s_lshl_b32 s28, s26, 5
	global_load_dwordx4 v[28:31], v[28:29], off
	s_ashr_i32 s25, s24, 31
	s_and_b32 s28, s28, 0xf80
	s_lshl_b64 s[24:25], s[24:25], 12
	s_or_b32 s24, s24, s28
	s_lshl_b32 s28, s27, 8
	s_waitcnt vmcnt(0)
	v_cvt_f16_f32_e32 v0, v0
	v_cvt_f16_f32_e32 v1, v1
	v_cvt_f16_f32_e32 v2, v2
	v_cvt_f16_f32_e32 v3, v3
	v_cndmask_b32_e64 v0, v0, 0, s[40:41]
	v_readlane_b32 s40, v255, 58
	v_cvt_f16_f32_e32 v4, v4
	v_cvt_f16_f32_e32 v5, v5
	v_cvt_f16_f32_e32 v6, v6
	v_cvt_f16_f32_e32 v7, v7
	v_cvt_f16_f32_e32 v8, v8
	v_cvt_f16_f32_e32 v9, v9
	v_cvt_f16_f32_e32 v10, v10
	v_cvt_f16_f32_e32 v11, v11
	v_cvt_f16_f32_e32 v12, v12
	v_cvt_f16_f32_e32 v13, v13
	v_cvt_f16_f32_e32 v14, v14
	v_cvt_f16_f32_e32 v15, v15
	v_cvt_f16_f32_e32 v16, v16
	v_cvt_f16_f32_e32 v17, v17
	v_cvt_f16_f32_e32 v18, v18
	v_cvt_f16_f32_e32 v19, v19
	v_cvt_f16_f32_e32 v20, v20
	v_cvt_f16_f32_e32 v21, v21
	v_cvt_f16_f32_e32 v22, v22
	v_cvt_f16_f32_e32 v23, v23
	v_readlane_b32 s41, v255, 59
	v_cndmask_b32_e64 v4, v4, 0, s[48:49]
	v_cndmask_b32_e64 v5, 0, v5, s[50:51]
	v_cndmask_b32_e64 v57, 0, v1, s[40:41]
	v_cndmask_b32_e64 v1, v2, 0, s[44:45]
	v_cndmask_b32_e64 v2, v3, 0, s[46:47]
	v_cndmask_b32_e64 v3, v6, 0, s[52:53]
	v_cndmask_b32_e64 v6, v7, 0, s[54:55]
	v_cndmask_b32_e64 v7, v8, 0, s[56:57]
	v_cndmask_b32_e64 v8, 0, v9, s[58:59]
	v_cndmask_b32_e64 v9, v10, 0, s[60:61]
	v_cndmask_b32_e64 v10, v11, 0, s[62:63]
	v_cndmask_b32_e64 v11, v12, 0, s[64:65]
	v_cndmask_b32_e64 v12, 0, v13, s[66:67]
	v_cndmask_b32_e64 v13, v14, 0, s[68:69]
	v_cndmask_b32_e64 v14, v15, 0, s[70:71]
	v_cndmask_b32_e64 v15, v16, 0, s[72:73]
	v_cndmask_b32_e64 v16, 0, v17, s[74:75]
	v_cndmask_b32_e64 v17, v18, 0, s[76:77]
	v_cndmask_b32_e64 v18, v19, 0, s[78:79]
	v_cndmask_b32_e64 v19, v20, 0, s[80:81]
	v_cndmask_b32_e64 v20, 0, v21, s[82:83]
	v_cndmask_b32_e64 v21, v22, 0, s[84:85]
	v_cndmask_b32_e64 v22, v23, 0, s[42:43]
	v_pack_b32_f16 v1, v1, v2
	v_pack_b32_f16 v0, v0, v57
	v_cvt_f16_f32_e32 v24, v24
	v_cvt_f16_f32_e32 v25, v25
	v_pack_b32_f16 v3, v3, v6
	v_pack_b32_f16 v2, v4, v5
	v_pack_b32_f16 v5, v9, v10
	v_pack_b32_f16 v4, v7, v8
	v_pack_b32_f16 v7, v13, v14
	v_pack_b32_f16 v6, v11, v12
	v_pack_b32_f16 v9, v17, v18
	v_pack_b32_f16 v8, v15, v16
	v_pack_b32_f16 v11, v21, v22
	v_pack_b32_f16 v10, v19, v20
	ds_write_b64 v67, v[0:1]
	ds_write_b64 v68, v[2:3]
	ds_write_b64 v69, v[4:5]
	ds_write_b64 v70, v[6:7]
	ds_write_b64 v71, v[8:9]
	ds_write_b64 v72, v[10:11]
	v_cvt_f16_f32_e32 v0, v26
	v_cvt_f16_f32_e32 v1, v27
	v_cndmask_b32_e64 v2, v24, 0, s[88:89]
	v_cndmask_b32_e64 v3, 0, v25, s[90:91]
	v_cndmask_b32_e64 v0, v0, 0, s[92:93]
	v_cndmask_b32_e64 v1, v1, 0, s[94:95]
	v_pack_b32_f16 v1, v0, v1
	v_pack_b32_f16 v0, v2, v3
	ds_write_b64 v73, v[0:1]
	v_cvt_f16_f32_e32 v0, v28
	v_cvt_f16_f32_e32 v1, v29
	v_cvt_f16_f32_e32 v2, v30
	v_cvt_f16_f32_e32 v3, v31
	v_cndmask_b32_e64 v0, v0, 0, s[96:97]
	v_cndmask_b32_e64 v4, 0, v1, s[4:5]
	v_cndmask_b32_e64 v1, v2, 0, s[6:7]
	v_cndmask_b32_e64 v2, v3, 0, s[8:9]
	v_pack_b32_f16 v1, v1, v2
	v_pack_b32_f16 v0, v0, v4
	ds_write_b64 v74, v[0:1]
	v_lshl_add_u64 v[0:1], s[24:25], 0, v[34:35]
	v_mov_b64_e32 v[2:3], s[0:1]
	v_mad_u64_u32 v[2:3], s[40:41], v0, s13, v[2:3]
	v_mad_i32_i24 v3, v1, s13, v3
	s_mov_b64 s[40:41], 0x2800
	v_lshl_add_u64 v[8:9], v[2:3], 0, s[40:41]
	v_lshl_add_u64 v[10:11], v[8:9], 0, v[168:169]
	global_load_dwordx4 v[84:87], v[10:11], off
	global_load_dwordx4 v[88:91], v[10:11], off offset:64
	global_load_dwordx4 v[92:95], v[10:11], off offset:128
	global_load_dwordx4 v[96:99], v[10:11], off offset:192
	global_load_dwordx4 v[100:103], v[10:11], off offset:256
	global_load_dwordx4 v[104:107], v[10:11], off offset:320
	global_load_dwordx4 v[108:111], v[10:11], off offset:384
	global_load_dwordx4 v[112:115], v[10:11], off offset:448
	global_load_dwordx4 v[116:119], v[10:11], off offset:512
	global_load_dwordx4 v[120:123], v[10:11], off offset:576
	global_load_dwordx4 v[124:127], v[10:11], off offset:640
	global_load_dwordx4 v[128:131], v[10:11], off offset:704
	global_load_dwordx4 v[132:135], v[10:11], off offset:768
	global_load_dwordx4 v[136:139], v[10:11], off offset:832
	global_load_dwordx4 v[140:143], v[10:11], off offset:896
	global_load_dwordx4 v[144:147], v[10:11], off offset:960
	s_lshl_b32 s40, s27, 7
	s_mov_b32 s27, 0x800000
	s_waitcnt vmcnt(9) lgkmcnt(0)
; __device__ __forceinline__ float bfe(const v4u& v, int e) { const unsigned w = v[e >> 1]; return (e & 1) ? __uint_as_float(w & 0xffff0000u) : __uint_as_float(w << 16); }
; __device__ __forceinline__ void mix_sgu(const bf16* h, const float* lng, const float* lnb, const float* sgw, const float* sgb, bf16* ycat, char* lds, int wg, int nwg) {
;     ...
;           for (int j = 0; j < 16; ++j) { const v4u vv = *(const v4u*)(vr + (4 * j + q) * 8);
; #pragma unroll
;               for (int e = 0; e < 8; ++e) { const float x = bfe(vv, e); s1 += x; s2 += x * x; } }
	v_lshlrev_b32_e32 v57, 16, v84
	v_and_b32_e32 v58, 0xffff0000, v84
	v_add_f32_e32 v83, 0, v57
	v_mul_f32_e32 v12, v58, v58
	v_lshlrev_b32_e32 v59, 16, v85
	v_add_f32_e32 v58, v83, v58
	v_fmac_f32_e32 v12, v57, v57
	v_and_b32_e32 v13, 0xffff0000, v85
	v_add_f32_e32 v57, v58, v59
	v_fmac_f32_e32 v12, v59, v59
	v_lshlrev_b32_e32 v60, 16, v86
	v_add_f32_e32 v57, v57, v13
	v_fmac_f32_e32 v12, v13, v13
	v_and_b32_e32 v14, 0xffff0000, v86
	v_add_f32_e32 v13, v57, v60
	v_fmac_f32_e32 v12, v60, v60
	v_lshlrev_b32_e32 v61, 16, v87
	v_add_f32_e32 v13, v13, v14
	v_fmac_f32_e32 v12, v14, v14
	v_and_b32_e32 v15, 0xffff0000, v87
	v_add_f32_e32 v13, v13, v61
	v_fmac_f32_e32 v12, v61, v61
	v_lshlrev_b32_e32 v62, 16, v88
	v_add_f32_e32 v13, v13, v15
	v_fmac_f32_e32 v12, v15, v15
	v_and_b32_e32 v16, 0xffff0000, v88
	v_add_f32_e32 v13, v13, v62
	v_fmac_f32_e32 v12, v62, v62
	v_lshlrev_b32_e32 v63, 16, v89
	v_add_f32_e32 v13, v13, v16
	v_fmac_f32_e32 v12, v16, v16
	v_and_b32_e32 v17, 0xffff0000, v89
	v_add_f32_e32 v13, v13, v63
	v_fmac_f32_e32 v12, v63, v63
	v_lshlrev_b32_e32 v77, 16, v90
	v_add_f32_e32 v13, v13, v17
	v_fmac_f32_e32 v12, v17, v17
	v_and_b32_e32 v18, 0xffff0000, v90
	v_add_f32_e32 v13, v13, v77
	v_fmac_f32_e32 v12, v77, v77
	v_lshlrev_b32_e32 v78, 16, v91
	v_add_f32_e32 v13, v13, v18
	v_fmac_f32_e32 v12, v18, v18
	v_and_b32_e32 v19, 0xffff0000, v91
	v_add_f32_e32 v13, v13, v78
	v_fmac_f32_e32 v12, v78, v78
	v_lshlrev_b32_e32 v79, 16, v92
	v_add_f32_e32 v13, v13, v19
	v_fmac_f32_e32 v12, v19, v19
	v_and_b32_e32 v20, 0xffff0000, v92
	v_add_f32_e32 v13, v13, v79
	v_fmac_f32_e32 v12, v79, v79
	v_lshlrev_b32_e32 v80, 16, v93
	v_add_f32_e32 v13, v13, v20
	v_fmac_f32_e32 v12, v20, v20
	v_and_b32_e32 v21, 0xffff0000, v93
	v_add_f32_e32 v13, v13, v80
	v_fmac_f32_e32 v12, v80, v80
	v_lshlrev_b32_e32 v81, 16, v94
	v_add_f32_e32 v13, v13, v21
	v_fmac_f32_e32 v12, v21, v21
	v_and_b32_e32 v22, 0xffff0000, v94
	v_add_f32_e32 v13, v13, v81
	v_fmac_f32_e32 v12, v81, v81
	v_lshlrev_b32_e32 v82, 16, v95
	v_add_f32_e32 v13, v13, v22
	v_fmac_f32_e32 v12, v22, v22
	v_add_f32_e32 v13, v13, v82
	v_fmac_f32_e32 v12, v82, v82
	v_and_b32_e32 v14, 0xffff0000, v95
	v_add_f32_e32 v13, v13, v14
	v_fmac_f32_e32 v12, v14, v14
	v_lshlrev_b32_e32 v14, 16, v96
	v_add_f32_e32 v13, v13, v14
	v_fmac_f32_e32 v12, v14, v14
	v_and_b32_e32 v14, 0xffff0000, v96
	v_add_f32_e32 v13, v13, v14
	v_fmac_f32_e32 v12, v14, v14
	v_lshlrev_b32_e32 v14, 16, v97
	v_add_f32_e32 v13, v13, v14
	v_fmac_f32_e32 v12, v14, v14
	v_and_b32_e32 v14, 0xffff0000, v97
	v_add_f32_e32 v13, v13, v14
	v_fmac_f32_e32 v12, v14, v14
	v_lshlrev_b32_e32 v14, 16, v98
	v_add_f32_e32 v13, v13, v14
	v_fmac_f32_e32 v12, v14, v14
	v_and_b32_e32 v14, 0xffff0000, v98
	v_add_f32_e32 v13, v13, v14
	v_fmac_f32_e32 v12, v14, v14
	v_lshlrev_b32_e32 v18, 16, v99
	v_add_f32_e32 v13, v13, v18
	v_fmac_f32_e32 v12, v18, v18
	v_and_b32_e32 v18, 0xffff0000, v99
	v_add_f32_e32 v13, v13, v18
	v_fmac_f32_e32 v12, v18, v18
	v_lshlrev_b32_e32 v18, 16, v100
	v_add_f32_e32 v13, v13, v18
	v_fmac_f32_e32 v12, v18, v18
	v_and_b32_e32 v18, 0xffff0000, v100
	v_add_f32_e32 v13, v13, v18
	v_fmac_f32_e32 v12, v18, v18
	v_lshlrev_b32_e32 v18, 16, v101
	v_add_f32_e32 v13, v13, v18
	v_fmac_f32_e32 v12, v18, v18
	v_and_b32_e32 v18, 0xffff0000, v101
	v_add_f32_e32 v13, v13, v18
	v_fmac_f32_e32 v12, v18, v18
	v_lshlrev_b32_e32 v18, 16, v102
	v_add_f32_e32 v13, v13, v18
	v_fmac_f32_e32 v12, v18, v18
	v_and_b32_e32 v18, 0xffff0000, v102
	v_add_f32_e32 v13, v13, v18
	v_fmac_f32_e32 v12, v18, v18
	v_lshlrev_b32_e32 v22, 16, v103
	v_add_f32_e32 v13, v13, v22
	v_fmac_f32_e32 v12, v22, v22
	v_and_b32_e32 v22, 0xffff0000, v103
	v_add_f32_e32 v13, v13, v22
	v_fmac_f32_e32 v12, v22, v22
	v_lshlrev_b32_e32 v22, 16, v104
	v_add_f32_e32 v13, v13, v22
	v_fmac_f32_e32 v12, v22, v22
	v_and_b32_e32 v4, 0xffff0000, v104
	v_add_f32_e32 v13, v13, v4
	v_fmac_f32_e32 v12, v4, v4
	v_lshlrev_b32_e32 v4, 16, v105
	v_add_f32_e32 v13, v13, v4
	v_fmac_f32_e32 v12, v4, v4
	v_and_b32_e32 v4, 0xffff0000, v105
	v_add_f32_e32 v5, v13, v4
	v_fmac_f32_e32 v12, v4, v4
	v_lshlrev_b32_e32 v4, 16, v106
	v_add_f32_e32 v5, v5, v4
	v_fmac_f32_e32 v12, v4, v4
	v_and_b32_e32 v4, 0xffff0000, v106
	v_add_f32_e32 v5, v5, v4
	v_fmac_f32_e32 v12, v4, v4
	v_lshlrev_b32_e32 v4, 16, v107
	v_add_f32_e32 v5, v5, v4
	v_fmac_f32_e32 v12, v4, v4
	v_and_b32_e32 v4, 0xffff0000, v107
	v_add_f32_e32 v5, v5, v4
	v_fmac_f32_e32 v12, v4, v4
	v_lshlrev_b32_e32 v4, 16, v108
	v_add_f32_e32 v5, v5, v4
	v_fmac_f32_e32 v12, v4, v4
	v_and_b32_e32 v0, 0xffff0000, v108
	v_add_f32_e32 v4, v5, v0
	v_fmac_f32_e32 v12, v0, v0
	v_lshlrev_b32_e32 v0, 16, v109
	v_add_f32_e32 v4, v4, v0
	v_fmac_f32_e32 v12, v0, v0
	v_and_b32_e32 v0, 0xffff0000, v109
	v_add_f32_e32 v1, v4, v0
	v_fmac_f32_e32 v12, v0, v0
	v_lshlrev_b32_e32 v0, 16, v110
	v_add_f32_e32 v1, v1, v0
	v_fmac_f32_e32 v12, v0, v0
	v_and_b32_e32 v0, 0xffff0000, v110
	v_add_f32_e32 v1, v1, v0
	v_fmac_f32_e32 v12, v0, v0
	v_lshlrev_b32_e32 v0, 16, v111
	v_add_f32_e32 v1, v1, v0
	v_fmac_f32_e32 v12, v0, v0
	v_and_b32_e32 v0, 0xffff0000, v111
	v_add_f32_e32 v1, v1, v0
	v_fmac_f32_e32 v12, v0, v0
	s_waitcnt vmcnt(5) lgkmcnt(0)
; __device__ __forceinline__ float bfe(const v4u& v, int e) { const unsigned w = v[e >> 1]; return (e & 1) ? __uint_as_float(w & 0xffff0000u) : __uint_as_float(w << 16); }
; __device__ __forceinline__ void mix_sgu(const bf16* h, const float* lng, const float* lnb, const float* sgw, const float* sgb, bf16* ycat, char* lds, int wg, int nwg) {
;     ...
;           for (int j = 0; j < 16; ++j) { const v4u vv = *(const v4u*)(vr + (4 * j + q) * 8);
; #pragma unroll
;               for (int e = 0; e < 8; ++e) { const float x = bfe(vv, e); s1 += x; s2 += x * x; } }
;           s1 += __shfl_xor(s1, 1); s1 += __shfl_xor(s1, 2); s2 += __shfl_xor(s2, 1); s2 += __shfl_xor(s2, 2);
;           const float mu = s1 * (1.f / 512.f), rstd = rsqrtf(fmaxf(s2 * (1.f / 512.f) - mu * mu, 0.f) + LN_EPS);
; #pragma unroll
;           for (int j = 0; j < 4; ++j) { const int c0 = 32 * q + 8 * j; const v4u vv = *(const v4u*)(vr + 128 * grp + c0);
	v_lshlrev_b32_e32 v0, 16, v112
	v_add_f32_e32 v1, v1, v0
	v_fmac_f32_e32 v12, v0, v0
	v_and_b32_e32 v0, 0xffff0000, v112
	v_add_f32_e32 v1, v1, v0
	v_fmac_f32_e32 v12, v0, v0
	v_lshlrev_b32_e32 v0, 16, v113
	v_add_f32_e32 v1, v1, v0
	v_fmac_f32_e32 v12, v0, v0
	v_and_b32_e32 v0, 0xffff0000, v113
	v_add_f32_e32 v1, v1, v0
	v_fmac_f32_e32 v12, v0, v0
	v_lshlrev_b32_e32 v0, 16, v114
	v_add_f32_e32 v1, v1, v0
	v_fmac_f32_e32 v12, v0, v0
	v_and_b32_e32 v0, 0xffff0000, v114
	v_add_f32_e32 v1, v1, v0
	v_lshlrev_b32_e32 v13, 16, v115
	v_fmac_f32_e32 v12, v0, v0
	v_add_f32_e32 v14, v1, v13
	v_fmac_f32_e32 v12, v13, v13
	v_and_b32_e32 v13, 0xffff0000, v115
	v_add_f32_e32 v14, v14, v13
	v_fmac_f32_e32 v12, v13, v13
	v_lshlrev_b32_e32 v13, 16, v116
	v_add_f32_e32 v14, v14, v13
	v_fmac_f32_e32 v12, v13, v13
	v_and_b32_e32 v13, 0xffff0000, v116
	v_add_f32_e32 v14, v14, v13
	v_fmac_f32_e32 v12, v13, v13
	v_lshlrev_b32_e32 v13, 16, v117
	v_add_f32_e32 v14, v14, v13
	v_fmac_f32_e32 v12, v13, v13
	v_and_b32_e32 v13, 0xffff0000, v117
	v_add_f32_e32 v14, v14, v13
	v_fmac_f32_e32 v12, v13, v13
	v_lshlrev_b32_e32 v13, 16, v118
	v_add_f32_e32 v14, v14, v13
	v_fmac_f32_e32 v12, v13, v13
	v_and_b32_e32 v13, 0xffff0000, v118
	v_add_f32_e32 v18, v14, v13
	v_fmac_f32_e32 v12, v13, v13
	v_lshlrev_b32_e32 v13, 16, v119
	v_add_f32_e32 v18, v18, v13
	v_fmac_f32_e32 v12, v13, v13
	v_and_b32_e32 v13, 0xffff0000, v119
	v_add_f32_e32 v18, v18, v13
	v_fmac_f32_e32 v12, v13, v13
	v_lshlrev_b32_e32 v13, 16, v120
	v_add_f32_e32 v18, v18, v13
	v_fmac_f32_e32 v12, v13, v13
	v_and_b32_e32 v13, 0xffff0000, v120
	v_add_f32_e32 v18, v18, v13
	v_fmac_f32_e32 v12, v13, v13
	v_lshlrev_b32_e32 v13, 16, v121
	v_add_f32_e32 v18, v18, v13
	v_fmac_f32_e32 v12, v13, v13
	v_and_b32_e32 v13, 0xffff0000, v121
	v_add_f32_e32 v18, v18, v13
	v_fmac_f32_e32 v12, v13, v13
	v_lshlrev_b32_e32 v13, 16, v122
	v_add_f32_e32 v18, v18, v13
	v_fmac_f32_e32 v12, v13, v13
	v_and_b32_e32 v13, 0xffff0000, v122
	v_add_f32_e32 v22, v18, v13
	v_fmac_f32_e32 v12, v13, v13
	v_lshlrev_b32_e32 v13, 16, v123
	v_add_f32_e32 v22, v22, v13
	v_fmac_f32_e32 v12, v13, v13
	v_and_b32_e32 v13, 0xffff0000, v123
	v_add_f32_e32 v22, v22, v13
	v_fmac_f32_e32 v12, v13, v13
	v_lshlrev_b32_e32 v13, 16, v124
	v_add_f32_e32 v22, v22, v13
	v_and_b32_e32 v4, 0xffff0000, v124
	v_fmac_f32_e32 v12, v13, v13
	v_add_f32_e32 v13, v22, v4
	v_fmac_f32_e32 v12, v4, v4
	v_lshlrev_b32_e32 v4, 16, v125
	v_add_f32_e32 v13, v13, v4
	v_fmac_f32_e32 v12, v4, v4
	v_and_b32_e32 v4, 0xffff0000, v125
	v_add_f32_e32 v5, v13, v4
	v_fmac_f32_e32 v12, v4, v4
	v_lshlrev_b32_e32 v4, 16, v126
	v_add_f32_e32 v5, v5, v4
	v_fmac_f32_e32 v12, v4, v4
	v_and_b32_e32 v4, 0xffff0000, v126
	v_add_f32_e32 v5, v5, v4
	v_fmac_f32_e32 v12, v4, v4
	v_lshlrev_b32_e32 v4, 16, v127
	v_add_f32_e32 v5, v5, v4
	v_fmac_f32_e32 v12, v4, v4
	v_and_b32_e32 v4, 0xffff0000, v127
	v_add_f32_e32 v5, v5, v4
	v_fmac_f32_e32 v12, v4, v4
	s_waitcnt vmcnt(1) lgkmcnt(0)
	v_lshlrev_b32_e32 v4, 16, v128
	v_add_f32_e32 v5, v5, v4
	v_fmac_f32_e32 v12, v4, v4
	v_and_b32_e32 v0, 0xffff0000, v128
	v_add_f32_e32 v4, v5, v0
	v_fmac_f32_e32 v12, v0, v0
	v_lshlrev_b32_e32 v0, 16, v129
	v_add_f32_e32 v4, v4, v0
	v_fmac_f32_e32 v12, v0, v0
	v_and_b32_e32 v0, 0xffff0000, v129
	v_add_f32_e32 v1, v4, v0
	v_fmac_f32_e32 v12, v0, v0
	v_lshlrev_b32_e32 v0, 16, v130
	v_add_f32_e32 v1, v1, v0
	v_fmac_f32_e32 v12, v0, v0
	v_and_b32_e32 v0, 0xffff0000, v130
	v_add_f32_e32 v1, v1, v0
	v_fmac_f32_e32 v12, v0, v0
	v_lshlrev_b32_e32 v0, 16, v131
	v_add_f32_e32 v1, v1, v0
	v_fmac_f32_e32 v12, v0, v0
	v_and_b32_e32 v0, 0xffff0000, v131
	v_add_f32_e32 v1, v1, v0
	v_fmac_f32_e32 v12, v0, v0
	v_lshlrev_b32_e32 v0, 16, v132
	v_add_f32_e32 v1, v1, v0
	v_and_b32_e32 v4, 0xffff0000, v132
	v_fmac_f32_e32 v12, v0, v0
	v_add_f32_e32 v5, v1, v4
	v_fmac_f32_e32 v12, v4, v4
	v_lshlrev_b32_e32 v4, 16, v133
	v_add_f32_e32 v5, v5, v4
	v_fmac_f32_e32 v12, v4, v4
	v_and_b32_e32 v4, 0xffff0000, v133
	v_add_f32_e32 v5, v5, v4
	v_fmac_f32_e32 v12, v4, v4
	v_lshlrev_b32_e32 v4, 16, v134
	v_add_f32_e32 v5, v5, v4
	v_fmac_f32_e32 v12, v4, v4
	v_and_b32_e32 v4, 0xffff0000, v134
	v_add_f32_e32 v5, v5, v4
	v_fmac_f32_e32 v12, v4, v4
	v_lshlrev_b32_e32 v4, 16, v135
	v_add_f32_e32 v5, v5, v4
	v_fmac_f32_e32 v12, v4, v4
	v_and_b32_e32 v4, 0xffff0000, v135
	v_add_f32_e32 v5, v5, v4
	v_fmac_f32_e32 v12, v4, v4
	v_lshlrev_b32_e32 v4, 16, v136
	v_add_f32_e32 v5, v5, v4
	v_fmac_f32_e32 v12, v4, v4
	v_and_b32_e32 v4, 0xffff0000, v136
	v_add_f32_e32 v5, v5, v4
	v_fmac_f32_e32 v12, v4, v4
	v_lshlrev_b32_e32 v4, 16, v137
	v_add_f32_e32 v5, v5, v4
	v_fmac_f32_e32 v12, v4, v4
	v_and_b32_e32 v4, 0xffff0000, v137
	v_add_f32_e32 v5, v5, v4
	v_fmac_f32_e32 v12, v4, v4
	v_lshlrev_b32_e32 v4, 16, v138
	v_add_f32_e32 v5, v5, v4
	v_fmac_f32_e32 v12, v4, v4
	v_and_b32_e32 v4, 0xffff0000, v138
	v_add_f32_e32 v5, v5, v4
	v_fmac_f32_e32 v12, v4, v4
	v_lshlrev_b32_e32 v4, 16, v139
	v_add_f32_e32 v5, v5, v4
	v_fmac_f32_e32 v12, v4, v4
	v_and_b32_e32 v4, 0xffff0000, v139
	v_add_f32_e32 v5, v5, v4
	v_fmac_f32_e32 v12, v4, v4
	v_lshlrev_b32_e32 v4, 16, v140
	v_add_f32_e32 v5, v5, v4
	v_and_b32_e32 v13, 0xffff0000, v140
	v_fmac_f32_e32 v12, v4, v4
	v_add_f32_e32 v22, v5, v13
	v_lshl_add_u64 v[4:5], v[8:9], 0, s[28:29]
	v_lshlrev_b32_e32 v6, 1, v36
	v_mov_b32_e32 v7, v169
	v_lshl_add_u64 v[30:31], v[4:5], 0, v[6:7]
	global_load_dwordx4 v[4:7], v[30:31], off
	v_or_b32_e32 v8, s40, v36
	v_lshlrev_b32_e32 v57, 2, v8
	global_load_dwordx4 v[8:11], v57, s[36:37] offset:16
	global_load_dwordx4 v[14:17], v57, s[36:37]
	global_load_dwordx4 v[18:21], v57, s[14:15] offset:16
	global_load_dwordx4 v[26:29], v57, s[14:15]
	v_fmac_f32_e32 v12, v13, v13
	v_lshlrev_b32_e32 v13, 16, v141
	v_add_f32_e32 v22, v22, v13
	v_lshlrev_b32_e32 v59, 16, v142
	v_and_b32_e32 v58, 0xffff0000, v141
	v_fmac_f32_e32 v12, v13, v13
	v_add_f32_e32 v13, v22, v58
	v_pk_mul_f32 v[22:23], v[58:59], v[58:59]
	s_mov_b32 s28, 0x3b000000
	v_add_f32_e32 v12, v22, v12
	v_add_f32_e32 v22, v13, v59
	v_add_f32_e32 v58, v23, v12
	v_lshlrev_b32_e32 v13, 16, v143
	v_and_b32_e32 v12, 0xffff0000, v142
	v_add_f32_e32 v24, v22, v12
	v_pk_mul_f32 v[22:23], v[12:13], v[12:13]
	s_nop 0
	v_add_f32_e32 v12, v22, v58
	v_add_f32_e32 v22, v24, v13
	v_add_f32_e32 v24, v23, v12
	v_and_b32_e32 v13, 0xffff0000, v143
	v_add_f32_e32 v25, v22, v13
	s_waitcnt vmcnt(0) lgkmcnt(0)
; __device__ __forceinline__ float bfe(const v4u& v, int e) { const unsigned w = v[e >> 1]; return (e & 1) ? __uint_as_float(w & 0xffff0000u) : __uint_as_float(w << 16); }
; __device__ __forceinline__ void mix_sgu(const bf16* h, const float* lng, const float* lnb, const float* sgw, const float* sgb, bf16* ycat, char* lds, int wg, int nwg) {
;     ...
;               for (int e = 0; e < 8; ++e) { const float x = bfe(vv, e); s1 += x; s2 += x * x; } }
;           s1 += __shfl_xor(s1, 1); s1 += __shfl_xor(s1, 2); s2 += __shfl_xor(s2, 1); s2 += __shfl_xor(s2, 2);
;           const float mu = s1 * (1.f / 512.f), rstd = rsqrtf(fmaxf(s2 * (1.f / 512.f) - mu * mu, 0.f) + LN_EPS);
; #pragma unroll
;           for (int j = 0; j < 4; ++j) { const int c0 = 32 * q + 8 * j; const v4u vv = *(const v4u*)(vr + 128 * grp + c0);
; #pragma unroll
;               for (int e = 0; e < 8; ++e) { const float y = (bfe(vv, e) - mu) * rstd * lng[128 * grp + c0 + e] + lnb[128 * grp + c0 + e]; *(_Float16*)(lds + 36864 + (c0 + e) * 288 + row * 2) = (_Float16)y; } } }
	v_lshlrev_b32_e32 v12, 16, v144
	v_pk_mul_f32 v[22:23], v[12:13], v[12:13]
	s_nop 0
	v_add_f32_e32 v13, v23, v24
	v_add_f32_e32 v23, v25, v12
	v_add_f32_e32 v24, v22, v13
	v_lshlrev_b32_e32 v13, 16, v145
	v_and_b32_e32 v12, 0xffff0000, v144
	v_add_f32_e32 v0, v23, v12
	v_pk_mul_f32 v[22:23], v[12:13], v[12:13]
	v_add_f32_e32 v0, v0, v13
	v_add_f32_e32 v12, v22, v24
	v_add_f32_e32 v22, v23, v12
	v_lshlrev_b32_e32 v13, 16, v146
	v_and_b32_e32 v12, 0xffff0000, v145
	v_add_f32_e32 v23, v0, v12
	v_pk_mul_f32 v[0:1], v[12:13], v[12:13]
	v_add_f32_e32 v12, v23, v13
	v_add_f32_e32 v0, v0, v22
	v_add_f32_e32 v22, v1, v0
	v_lshlrev_b32_e32 v1, 16, v147
	v_and_b32_e32 v0, 0xffff0000, v146
	v_add_f32_e32 v2, v12, v0
	v_pk_mul_f32 v[12:13], v[0:1], v[0:1]
	v_and_b32_e32 v3, 0xffff0000, v147
	v_add_f32_e32 v0, v12, v22
	v_add_f32_e32 v1, v2, v1
	v_add_f32_e32 v2, v13, v0
	v_mul_f32_e32 v0, v3, v3
	v_pk_add_f32 v[0:1], v[0:1], v[2:3]
	ds_bpermute_b32 v3, v37, v1
	ds_bpermute_b32 v2, v37, v0
	s_waitcnt lgkmcnt(0)
	v_pk_add_f32 v[0:1], v[0:1], v[2:3]
	ds_bpermute_b32 v3, v64, v1
	ds_bpermute_b32 v2, v64, v0
	s_waitcnt lgkmcnt(0)
	v_pk_add_f32 v[0:1], v[0:1], v[2:3]
	s_nop 0
	v_pk_mul_f32 v[24:25], v[0:1], s[28:29] op_sel_hi:[1,0]
	s_nop 0
	v_fma_f32 v0, -v25, v25, v24
	v_max_f32_e32 v0, 0, v0
	v_add_f32_e32 v0, 0x3727c5ac, v0
	v_mul_f32_e32 v1, 0x4b800000, v0
	v_cmp_gt_f32_e32 vcc, s27, v0
	s_nop 1
	v_cndmask_b32_e32 v0, v0, v1, vcc
	v_rsq_f32_e32 v0, v0
	s_nop 0
	v_mul_f32_e32 v1, 0x45800000, v0
	v_cndmask_b32_e32 v24, v0, v1, vcc
	v_lshlrev_b32_e32 v0, 16, v4
	v_sub_f32_e32 v0, v0, v25
	v_mul_f32_e32 v0, v0, v24
	v_fma_mixlo_f16 v0, v14, v0, v26
	ds_write_b16 v75, v0 offset:36864
	v_and_b32_e32 v0, 0xffff0000, v4
	v_sub_f32_e32 v0, v0, v25
	v_mul_f32_e32 v0, v0, v24
	v_fma_mixlo_f16 v0, v15, v0, v27
	ds_write_b16 v75, v0 offset:37152
	v_lshlrev_b32_e32 v0, 16, v5
	v_sub_f32_e32 v0, v0, v25
	v_mul_f32_e32 v0, v0, v24
	v_fma_mixlo_f16 v0, v16, v0, v28
	ds_write_b16 v75, v0 offset:37440
	v_and_b32_e32 v0, 0xffff0000, v5
	v_sub_f32_e32 v0, v0, v25
	v_mul_f32_e32 v0, v0, v24
	v_fma_mixlo_f16 v0, v17, v0, v29
	ds_write_b16 v75, v0 offset:37728
	v_lshlrev_b32_e32 v0, 16, v6
	v_sub_f32_e32 v0, v0, v25
	v_mul_f32_e32 v0, v0, v24
	v_fma_mixlo_f16 v0, v8, v0, v18
	ds_write_b16 v75, v0 offset:38016
	v_and_b32_e32 v0, 0xffff0000, v6
	v_sub_f32_e32 v0, v0, v25
	v_mul_f32_e32 v0, v0, v24
	v_fma_mixlo_f16 v0, v9, v0, v19
	ds_write_b16 v75, v0 offset:38304
	v_lshlrev_b32_e32 v0, 16, v7
	v_sub_f32_e32 v0, v0, v25
	v_mul_f32_e32 v0, v0, v24
	v_fma_mixlo_f16 v0, v10, v0, v20
	ds_write_b16 v75, v0 offset:38592
	v_and_b32_e32 v0, 0xffff0000, v7
	v_sub_f32_e32 v0, v0, v25
	v_mul_f32_e32 v0, v0, v24
	v_fma_mixlo_f16 v0, v11, v0, v21
	ds_write_b16 v75, v0 offset:38880
	global_load_dwordx4 v[0:3], v[30:31], off offset:16
	global_load_dwordx4 v[4:7], v57, s[14:15] offset:32
	global_load_dwordx4 v[8:11], v57, s[36:37] offset:32
	global_load_dwordx4 v[12:15], v57, s[36:37] offset:48
	global_load_dwordx4 v[16:19], v57, s[14:15] offset:48
	v_readlane_b32 vcc_lo, v255, 54
	v_readlane_b32 vcc_hi, v255, 55
	s_andn2_b64 vcc, exec, vcc
	s_waitcnt vmcnt(0) lgkmcnt(0)
	v_lshlrev_b32_e32 v20, 16, v0
	v_and_b32_e32 v0, 0xffff0000, v0
	v_sub_f32_e32 v20, v20, v25
	v_sub_f32_e32 v0, v0, v25
	v_mul_f32_e32 v20, v20, v24
	v_mul_f32_e32 v0, v0, v24
	v_fma_mixlo_f16 v4, v8, v20, v4
	v_fma_mixlo_f16 v0, v9, v0, v5
	ds_write_b16 v76, v4 offset:36864
	ds_write_b16 v75, v0 offset:39456
	v_lshlrev_b32_e32 v0, 16, v1
	v_sub_f32_e32 v0, v0, v25
	v_mul_f32_e32 v0, v0, v24
	v_fma_mixlo_f16 v0, v10, v0, v6
	ds_write_b16 v75, v0 offset:39744
	v_and_b32_e32 v0, 0xffff0000, v1
	v_sub_f32_e32 v0, v0, v25
	v_mul_f32_e32 v0, v0, v24
	v_fma_mixlo_f16 v0, v11, v0, v7
	ds_write_b16 v75, v0 offset:40032
	v_lshlrev_b32_e32 v0, 16, v2
	v_sub_f32_e32 v0, v0, v25
	v_mul_f32_e32 v0, v0, v24
	v_fma_mixlo_f16 v0, v12, v0, v16
	ds_write_b16 v75, v0 offset:40320
	v_and_b32_e32 v0, 0xffff0000, v2
	v_sub_f32_e32 v0, v0, v25
	v_mul_f32_e32 v0, v0, v24
	v_fma_mixlo_f16 v0, v13, v0, v17
	ds_write_b16 v75, v0 offset:40608
	v_lshlrev_b32_e32 v0, 16, v3
	v_sub_f32_e32 v0, v0, v25
	v_mul_f32_e32 v0, v0, v24
	v_fma_mixlo_f16 v0, v14, v0, v18
	ds_write_b16 v75, v0 offset:40896
	v_and_b32_e32 v0, 0xffff0000, v3
	v_sub_f32_e32 v0, v0, v25
	v_mul_f32_e32 v0, v0, v24
	v_fma_mixlo_f16 v0, v15, v0, v19
	ds_write_b16 v75, v0 offset:41184
	global_load_dwordx4 v[0:3], v[30:31], off offset:32
	global_load_dwordx4 v[4:7], v57, s[14:15] offset:64
	global_load_dwordx4 v[8:11], v57, s[36:37] offset:64
	global_load_dwordx4 v[12:15], v57, s[36:37] offset:80
	global_load_dwordx4 v[16:19], v57, s[14:15] offset:80
	s_waitcnt vmcnt(0) lgkmcnt(0)
; __device__ __forceinline__ float bfe(const v4u& v, int e) { const unsigned w = v[e >> 1]; return (e & 1) ? __uint_as_float(w & 0xffff0000u) : __uint_as_float(w << 16); }
; __device__ __forceinline__ void mix_sgu(const bf16* h, const float* lng, const float* lnb, const float* sgw, const float* sgb, bf16* ycat, char* lds, int wg, int nwg) {
;     ...
;           for (int j = 0; j < 4; ++j) { const int c0 = 32 * q + 8 * j; const v4u vv = *(const v4u*)(vr + 128 * grp + c0);
; #pragma unroll
;               for (int e = 0; e < 8; ++e) { const float y = (bfe(vv, e) - mu) * rstd * lng[128 * grp + c0 + e] + lnb[128 * grp + c0 + e]; *(_Float16*)(lds + 36864 + (c0 + e) * 288 + row * 2) = (_Float16)y; } } }
;         __syncthreads();
;         pg8::f32x4 acc[8];
; #pragma unroll
;         for (int nb = 0; nb < 8; ++nb) acc[nb] = (pg8::f32x4){0.f, 0.f, 0.f, 0.f};
	v_lshlrev_b32_e32 v20, 16, v0
	v_and_b32_e32 v0, 0xffff0000, v0
	v_sub_f32_e32 v20, v20, v25
	v_sub_f32_e32 v0, v0, v25
	v_mul_f32_e32 v20, v20, v24
	v_mul_f32_e32 v0, v0, v24
	v_fma_mixlo_f16 v4, v8, v20, v4
	v_fma_mixlo_f16 v0, v9, v0, v5
	ds_write_b16 v76, v4 offset:39168
	ds_write_b16 v75, v0 offset:41760
	v_lshlrev_b32_e32 v0, 16, v1
	v_sub_f32_e32 v0, v0, v25
	v_mul_f32_e32 v0, v0, v24
	v_fma_mixlo_f16 v0, v10, v0, v6
	ds_write_b16 v75, v0 offset:42048
	v_and_b32_e32 v0, 0xffff0000, v1
	v_sub_f32_e32 v0, v0, v25
	v_mul_f32_e32 v0, v0, v24
	v_fma_mixlo_f16 v0, v11, v0, v7
	ds_write_b16 v75, v0 offset:42336
	v_lshlrev_b32_e32 v0, 16, v2
	v_sub_f32_e32 v0, v0, v25
	v_mul_f32_e32 v0, v0, v24
	v_fma_mixlo_f16 v0, v12, v0, v16
	ds_write_b16 v75, v0 offset:42624
	v_and_b32_e32 v0, 0xffff0000, v2
	v_sub_f32_e32 v0, v0, v25
	v_mul_f32_e32 v0, v0, v24
	v_fma_mixlo_f16 v0, v13, v0, v17
	ds_write_b16 v75, v0 offset:42912
	v_lshlrev_b32_e32 v0, 16, v3
	v_sub_f32_e32 v0, v0, v25
	v_mul_f32_e32 v0, v0, v24
	v_fma_mixlo_f16 v0, v14, v0, v18
	ds_write_b16 v75, v0 offset:43200
	v_and_b32_e32 v0, 0xffff0000, v3
	v_sub_f32_e32 v0, v0, v25
	v_mul_f32_e32 v0, v0, v24
	v_fma_mixlo_f16 v0, v15, v0, v19
	ds_write_b16 v75, v0 offset:43488
	global_load_dwordx4 v[4:7], v[30:31], off offset:48
	global_load_dwordx4 v[8:11], v57, s[14:15] offset:96
	global_load_dwordx4 v[12:15], v57, s[36:37] offset:96
	global_load_dwordx4 v[16:19], v57, s[36:37] offset:112
	global_load_dwordx4 v[20:23], v57, s[14:15] offset:112
	v_mov_b32_e32 v3, 0
	v_mov_b32_e32 v2, v3
	v_mov_b32_e32 v1, v3
	v_mov_b32_e32 v27, v3
	v_mov_b32_e32 v26, v3
	v_mov_b32_e32 v31, v3
	v_mov_b32_e32 v30, v3
	v_mov_b32_e32 v29, v3
	v_mov_b32_e32 v28, v3
	s_waitcnt vmcnt(0) lgkmcnt(0)
	v_lshlrev_b32_e32 v0, 16, v4
	v_sub_f32_e32 v0, v0, v25
	v_mul_f32_e32 v0, v0, v24
	v_fma_mixlo_f16 v0, v12, v0, v8
	ds_write_b16 v76, v0 offset:41472
	v_and_b32_e32 v0, 0xffff0000, v4
	v_sub_f32_e32 v0, v0, v25
	v_mul_f32_e32 v0, v0, v24
	v_fma_mixlo_f16 v0, v13, v0, v9
	ds_write_b16 v75, v0 offset:44064
	v_lshlrev_b32_e32 v0, 16, v5
	v_sub_f32_e32 v0, v0, v25
	v_mul_f32_e32 v0, v0, v24
	v_fma_mixlo_f16 v0, v14, v0, v10
	ds_write_b16 v75, v0 offset:44352
	v_and_b32_e32 v0, 0xffff0000, v5
	v_sub_f32_e32 v0, v0, v25
	v_mul_f32_e32 v0, v0, v24
	v_fma_mixlo_f16 v0, v15, v0, v11
	ds_write_b16 v75, v0 offset:44640
	v_lshlrev_b32_e32 v0, 16, v6
	v_sub_f32_e32 v0, v0, v25
	v_mul_f32_e32 v0, v0, v24
	v_fma_mixlo_f16 v0, v16, v0, v20
	ds_write_b16 v75, v0 offset:44928
	v_and_b32_e32 v0, 0xffff0000, v6
	v_sub_f32_e32 v0, v0, v25
	v_mul_f32_e32 v0, v0, v24
	v_fma_mixlo_f16 v0, v17, v0, v21
	ds_write_b16 v75, v0 offset:45216
	v_lshlrev_b32_e32 v0, 16, v7
	v_sub_f32_e32 v0, v0, v25
	v_mul_f32_e32 v0, v0, v24
	v_fma_mixlo_f16 v0, v18, v0, v22
	ds_write_b16 v75, v0 offset:45504
	v_and_b32_e32 v0, 0xffff0000, v7
	v_sub_f32_e32 v0, v0, v25
	v_mul_f32_e32 v0, v0, v24
	v_fma_mixlo_f16 v0, v19, v0, v23
	ds_write_b16 v75, v0 offset:45792
	v_mov_b32_e32 v0, v3
	v_mov_b32_e32 v7, v3
	v_mov_b32_e32 v6, v3
	v_mov_b32_e32 v5, v3
	v_mov_b32_e32 v4, v3
	v_mov_b32_e32 v11, v3
	v_mov_b32_e32 v10, v3
	v_mov_b32_e32 v9, v3
	v_mov_b32_e32 v8, v3
	v_mov_b32_e32 v15, v3
	v_mov_b32_e32 v14, v3
	v_mov_b32_e32 v13, v3
	v_mov_b32_e32 v12, v3
	v_mov_b32_e32 v19, v3
	v_mov_b32_e32 v18, v3
	v_mov_b32_e32 v17, v3
	v_mov_b32_e32 v16, v3
	v_mov_b32_e32 v23, v3
	v_mov_b32_e32 v22, v3
	v_mov_b32_e32 v21, v3
	v_mov_b32_e32 v20, v3
	v_mov_b32_e32 v25, v3
	v_mov_b32_e32 v24, v3
	s_waitcnt lgkmcnt(0)
	s_barrier
	s_cbranch_vccnz .LBB0_675
	v_mov_b32_e32 v0, 0
	v_mov_b32_e32 v57, v65
	v_mov_b32_e32 v58, v66
	v_readlane_b32 s27, v255, 60
	v_mov_b32_e32 v1, v0
	v_mov_b32_e32 v2, v0
	v_mov_b32_e32 v3, v0
	v_mov_b32_e32 v28, v0
	v_mov_b32_e32 v29, v0
	v_mov_b32_e32 v30, v0
	v_mov_b32_e32 v31, v0
	v_mov_b32_e32 v24, v0
	v_mov_b32_e32 v25, v0
	v_mov_b32_e32 v26, v0
	v_mov_b32_e32 v27, v0
	v_mov_b32_e32 v20, v0
	v_mov_b32_e32 v21, v0
	v_mov_b32_e32 v22, v0
	v_mov_b32_e32 v23, v0
	v_mov_b32_e32 v16, v0
	v_mov_b32_e32 v17, v0
	v_mov_b32_e32 v18, v0
	v_mov_b32_e32 v19, v0
	v_mov_b32_e32 v12, v0
	v_mov_b32_e32 v13, v0
	v_mov_b32_e32 v14, v0
	v_mov_b32_e32 v15, v0
	v_mov_b32_e32 v8, v0
	v_mov_b32_e32 v9, v0
	v_mov_b32_e32 v10, v0
	v_mov_b32_e32 v11, v0
	v_mov_b32_e32 v4, v0
	v_mov_b32_e32 v5, v0
	v_mov_b32_e32 v6, v0
	v_mov_b32_e32 v7, v0
